# XCD-local grid barrier (no L2 write-back / cross-XCC hop) at the 4 seams per layer whose producer and consumer tiles share an XCD; placement verified at run time, else full barrier
# speedup vs baseline: 1.0283x; 1.0228x over previous
; #define LAS __attribute__((address_space(3)))
; __device__ __forceinline__ unsigned xb_xcc_id() { return (unsigned)__builtin_amdgcn_s_getreg((3 << 11) | 20) & 0xFu; }
; __global__ void __launch_bounds__(NTHREADS, 2) mega_fwd(Args args) {
;     extern __shared__ __attribute__((aligned(16))) unsigned char lds[];
;     cg::grid_group grid = cg::this_grid();
;     ...
;     if (threadIdx.x < 16) ((volatile LAS unsigned*)((LAS unsigned char*)lds + LDS_MISC))[threadIdx.x] = 0u;
;     __syncthreads();
_Z8mega_fwd4Args:
	s_mov_b64 s[90:91], s[0:1]
	s_load_dwordx2 s[56:57], s[0:1], 0xc8
	s_add_u32 s0, s90, 0xc8
	s_addc_u32 s1, s91, 0
	v_and_b32_e32 v203, 0x3ff, v0
	v_writelane_b32 v255, s0, 0
	s_mov_b32 s83, s2
	v_cmp_gt_u32_e32 vcc, 16, v203
	v_writelane_b32 v255, s1, 1
	s_and_saveexec_b64 s[4:5], vcc
	v_lshl_add_u32 v1, v203, 2, 0
	v_add_u32_e32 v1, 0x22000, v1
	v_mov_b32_e32 v2, 0
	ds_write_b32 v1, v2
	s_or_b64 exec, exec, s[4:5]
	s_waitcnt lgkmcnt(0)
	s_barrier
	s_load_dwordx4 s[4:7], s[90:91], 0x0
	s_load_dwordx4 s[92:95], s[90:91], 0x40
	s_cmp_lt_u32 s57, 2
	s_cselect_b64 s[0:1], -1, 0
	v_writelane_b32 v255, s0, 2
	v_lshrrev_b32_e32 v1, 20, v0
	v_lshrrev_b32_e32 v0, 10, v0
	v_writelane_b32 v255, s1, 3
	v_or_b32_e32 v0, v0, v1
	s_movk_i32 s0, 0x3ff
	v_and_or_b32 v0, v0, s0, v203
	s_waitcnt lgkmcnt(0)
	s_add_u32 s0, s4, 0xc00
	v_writelane_b32 v255, s0, 4
	s_mov_b64 s[2:3], s[6:7]
	v_writelane_b32 v255, s0, 5
	s_mov_b32 s69, 0
	v_mbcnt_lo_u32_b32 v1, -1, 0
	v_writelane_b32 v255, s1, 6
	v_writelane_b32 v255, s2, 7
	v_writelane_b32 v255, s3, 8
	s_addc_u32 s0, s5, 0
	v_writelane_b32 v255, s0, 9
	s_load_dwordx2 s[0:1], s[90:91], 0x60
	s_load_dwordx4 s[4:7], s[90:91], 0xb8
	v_mov_b32_e32 v193, 0
	v_mov_b32_e32 v212, 0x358637bd
	s_mov_b32 s89, 0xf800000
	s_waitcnt lgkmcnt(0)
	s_getreg_b32 s100, hwreg(HW_REG_XCC_ID, 0, 4)
	s_add_i32 s100, s100, 1
	s_lshl_b32 s101, s83, 2
	s_add_i32 s101, s101, 0xe208000
	v_mov_b32_e32 v245, s101
	v_mov_b32_e32 v246, s100
	global_store_dword v245, v246, s[6:7]
	s_mov_b32 s100, 0
	v_writelane_b32 v255, s0, 10
	v_mov_b32_e32 v213, 0x260
	v_mov_b32_e32 v244, 1
	v_writelane_b32 v255, s1, 11
	s_load_dwordx2 s[0:1], s[90:91], 0x70
	s_mov_b32 s81, 0x10000
	s_mov_b32 s57, 0xbfb8aa3b
	s_movk_i32 s3, 0x1600
	s_mov_b32 s73, 0x80000
	s_waitcnt lgkmcnt(0)
	v_writelane_b32 v255, s0, 12
	s_mov_b32 s33, 0x90000
	s_mov_b32 s80, 0xa0000
	v_writelane_b32 v255, s1, 13
	s_load_dwordx2 s[0:1], s[90:91], 0x50
	s_mov_b32 s96, 0xb0000
	s_mov_b32 s97, 0x800000
	s_mov_b32 s52, 0x3f317217
	s_mov_b32 s53, 0x7f800000
	s_waitcnt lgkmcnt(0)
	v_writelane_b32 v255, s0, 14
	s_mov_b32 s54, 0x40000
	s_mov_b32 s55, 0x48000
	v_writelane_b32 v255, s1, 15
	v_cmp_eq_u32_e64 s[0:1], 0, v0
	s_mov_b32 s86, 0x50000
	s_mov_b32 s87, 0x58000
	v_writelane_b32 v255, s0, 16
	v_mbcnt_hi_u32_b32 v215, -1, v1
	v_mov_b64_e32 v[242:243], 0x580
	v_writelane_b32 v255, s1, 17
	s_mov_b32 s0, s69
	v_writelane_b32 v255, s0, 18
	v_mov_b64_e32 v[196:197], 0x57f
	v_mov_b64_e32 v[198:199], 0x100
	v_writelane_b32 v255, s1, 19
	v_writelane_b32 v255, s4, 20
	v_mov_b64_e32 v[200:201], 0xff
	v_mov_b32_e32 v216, 0x41b17218
	v_writelane_b32 v255, s5, 21
	v_writelane_b32 v255, s6, 22
	v_writelane_b32 v255, s7, 23
	v_writelane_b32 v255, s90, 24
	v_mov_b32_e32 v217, 0xff800000
	s_mov_b32 s88, 0x41000000
	v_writelane_b32 v255, s91, 25
	v_writelane_b32 v255, s83, 26
	v_writelane_b32 v255, s92, 27
	s_mov_b64 s[44:45], -1
	s_mov_b64 s[76:77], 0x80
	v_writelane_b32 v255, s93, 28
	v_writelane_b32 v255, s94, 29
	s_mov_b64 s[46:47], 0x20000
	s_mov_b64 s[58:59], 0xba40000
	s_mov_b64 s[62:63], 0xca20000
	v_writelane_b32 v255, s95, 30
	s_branch .LBB0_6

; #define LAS __attribute__((address_space(3)))
; #define GSYNC() do { LAS unsigned char* l_ = (LAS unsigned char*)lds; asm volatile("" : "+s"(l_)); unsigned char* w_ = args.ws; asm volatile("" : "+s"(w_)); int t_ = threadIdx.x; asm volatile("" : "+v"(t_)); xcd_barrier((unsigned*)(w_ + WS_CTL), (volatile LAS unsigned*)(l_ + LDS_MISC), __builtin_amdgcn_readfirstlane(t_ >> 6), t_ & 63); } while (0)
; __global__ void __launch_bounds__(NTHREADS, 2) mega_fwd(Args args) {
;     ...
;     if (threadIdx.x < 16) ((volatile LAS unsigned*)((LAS unsigned char*)lds + LDS_MISC))[threadIdx.x] = 0u;
;     __syncthreads();
;     for (int l = 0; l < DEPTH; ++l) {
;     ...
;         { PHASE_PTRS MKFRAME
;         prologue(F, args, l); }
;     ...
;         if (gridDim.y > 1) grid.sync(); else GSYNC();
.LBB0_134:
	s_mov_b64 s[4:5], 0
	s_waitcnt lgkmcnt(0)
	s_barrier
	v_readlane_b32 s100, v255, 22
	v_readlane_b32 s101, v255, 23
	v_lshlrev_b32_e32 v245, 2, v215
	v_and_b32_e32 v246, 28, v245
	v_add_u32_e32 v245, 0xe208000, v245
	v_add_u32_e32 v246, 0xe208000, v246
	s_nop 3
	global_load_dword v247, v246, s[100:101]
	global_load_dword v248, v245, s[100:101]
	global_load_dword v249, v245, s[100:101] offset:256
	global_load_dword v250, v245, s[100:101] offset:512
	global_load_dword v251, v245, s[100:101] offset:768
	s_waitcnt vmcnt(0)
	v_xor_b32_e32 v248, v248, v247
	v_xor_b32_e32 v249, v249, v247
	v_xor_b32_e32 v250, v250, v247
	v_xor_b32_e32 v251, v251, v247
	v_or3_b32 v248, v248, v249, v250
	v_or_b32_e32 v248, v248, v251
	v_cmp_ne_u32_e32 vcc, 0, v248
	s_nop 1
	s_cmp_eq_u64 vcc, 0
	s_cselect_b32 s100, 1, 0

; __device__ __forceinline__ unsigned xb_ld_u(unsigned* p) { return (unsigned)__builtin_amdgcn_readfirstlane((int)__hip_atomic_load(p, RLX_AGENT)); }
; __device__ __forceinline__ unsigned xb_add_u(unsigned* p, unsigned v, int lane) { unsigned r = 0u; if (lane == 0) r = __hip_atomic_fetch_add(p, v, RLX_AGENT); return (unsigned)__builtin_amdgcn_readfirstlane((int)r); }
; #define XB_SPIN_U(cond, bar) do { unsigned _sp = 0; while (cond) { __builtin_amdgcn_s_sleep(1); if (++_sp > XB_SPIN_CAP) { if (lane == 0) atomicAdd(&(bar)[XB_TMO], 1u); break; } } } while (0)
; __device__ __forceinline__ void xcd_barrier(unsigned* bar, volatile __attribute__((address_space(3))) unsigned* st, int wave, int lane) {
;     ...
;         const unsigned old = xb_add_u(&bar[XB_XSUB(x)], 1u, lane), gen = old / nloc;
;         if (old + 1u == (gen + 1u) * nloc) {
;             __builtin_amdgcn_fence(__ATOMIC_RELEASE, "agent");
;             asm volatile("s_waitcnt vmcnt(0)" ::: "memory");
;             const unsigned og = xb_add_u(&bar[XB_TOP], 1u, lane), tg = og / nx;
;             if (og + 1u == (tg + 1u) * nx) (void)xb_add_u(&bar[XB_TOPGEN], 1u, lane);
;             else XB_SPIN_U(xb_ld_u(&bar[XB_TOPGEN]) == tg, bar);
.LBB0_225:
	s_andn2_saveexec_b64 s[14:15], s[6:7]
	s_cbranch_execz .LBB0_254
	s_cmp_lg_u32 s100, 0
	s_cbranch_scc1 .Llight_1
	buffer_wbl2 sc1
	buffer_inv sc1
	s_waitcnt vmcnt(0)
	v_mov_b32_e32 v2, 0
	s_and_saveexec_b64 s[6:7], s[4:5]
	s_cbranch_execz .LBB0_228
	v_mov_b32_e32 v2, s12
	v_add_co_u32_e32 v2, vcc, 0xe203000, v2
	v_mov_b32_e32 v3, s13
	s_nop 0
	v_addc_co_u32_e32 v3, vcc, 0, v3, vcc
	flat_atomic_add v2, v[2:3], v244 offset:1024 sc0

; __device__ __forceinline__ unsigned xb_ld_u(unsigned* p) { return (unsigned)__builtin_amdgcn_readfirstlane((int)__hip_atomic_load(p, RLX_AGENT)); }
; __device__ __forceinline__ unsigned xb_add_u(unsigned* p, unsigned v, int lane) { unsigned r = 0u; if (lane == 0) r = __hip_atomic_fetch_add(p, v, RLX_AGENT); return (unsigned)__builtin_amdgcn_readfirstlane((int)r); }
; #define XB_SPIN_U(cond, bar) do { unsigned _sp = 0; while (cond) { __builtin_amdgcn_s_sleep(1); if (++_sp > XB_SPIN_CAP) { if (lane == 0) atomicAdd(&(bar)[XB_TMO], 1u); break; } } } while (0)
; __device__ __forceinline__ void xcd_barrier(unsigned* bar, volatile __attribute__((address_space(3))) unsigned* st, int wave, int lane) {
;     ...
;             __builtin_amdgcn_fence(__ATOMIC_ACQUIRE, "agent");
;             (void)xb_add_u(&bar[XB_XGEN(x)], 1u, lane);
;             asm volatile("s_waitcnt vmcnt(0)" ::: "memory");
;         } else {
;             XB_SPIN_U(xb_ld_u(&bar[XB_XGEN(x)]) == gen, bar);
;             __builtin_amdgcn_fence(__ATOMIC_ACQUIRE, "agent");
;             asm volatile("s_waitcnt vmcnt(0)" ::: "memory");
.LBB0_253:
	s_or_b64 exec, exec, s[6:7]
	s_waitcnt vmcnt(0)
	s_branch .LBB0_254
.Llight_1:
	buffer_inv sc1
	s_mov_b64 s[6:7], exec
	s_and_b64 exec, exec, s[4:5]
	s_cbranch_execz .Llight_1_s
	v_mov_b32_e32 v0, s1
	v_add_co_u32_e32 v0, vcc, 0x2400, v0
	v_mov_b32_e32 v1, s0
	s_nop 0
	v_addc_co_u32_e32 v1, vcc, 0, v1, vcc
	flat_atomic_add v[0:1], v244
.Llight_1_s:
	s_mov_b64 exec, s[6:7]
	s_waitcnt vmcnt(0)

; __device__ __forceinline__ unsigned xb_ld_u(unsigned* p) { return (unsigned)__builtin_amdgcn_readfirstlane((int)__hip_atomic_load(p, RLX_AGENT)); }
; __device__ __forceinline__ unsigned xb_add_u(unsigned* p, unsigned v, int lane) { unsigned r = 0u; if (lane == 0) r = __hip_atomic_fetch_add(p, v, RLX_AGENT); return (unsigned)__builtin_amdgcn_readfirstlane((int)r); }
; #define XB_SPIN_U(cond, bar) do { unsigned _sp = 0; while (cond) { __builtin_amdgcn_s_sleep(1); if (++_sp > XB_SPIN_CAP) { if (lane == 0) atomicAdd(&(bar)[XB_TMO], 1u); break; } } } while (0)
; __device__ __forceinline__ void xcd_barrier(unsigned* bar, volatile __attribute__((address_space(3))) unsigned* st, int wave, int lane) {
;     ...
;         const unsigned old = xb_add_u(&bar[XB_XSUB(x)], 1u, lane), gen = old / nloc;
;         if (old + 1u == (gen + 1u) * nloc) {
;             __builtin_amdgcn_fence(__ATOMIC_RELEASE, "agent");
;             asm volatile("s_waitcnt vmcnt(0)" ::: "memory");
;             const unsigned og = xb_add_u(&bar[XB_TOP], 1u, lane), tg = og / nx;
;             if (og + 1u == (tg + 1u) * nx) (void)xb_add_u(&bar[XB_TOPGEN], 1u, lane);
;             else XB_SPIN_U(xb_ld_u(&bar[XB_TOPGEN]) == tg, bar);
.LBB0_946:
	s_andn2_saveexec_b64 s[12:13], s[6:7]
	s_cbranch_execz .LBB0_975
	s_cmp_lg_u32 s100, 0
	s_cbranch_scc1 .Llight_7
	buffer_wbl2 sc1
	buffer_inv sc1
	s_waitcnt vmcnt(0)
	v_mov_b32_e32 v2, 0
	s_and_saveexec_b64 s[6:7], s[4:5]
	s_cbranch_execz .LBB0_949
	v_mov_b32_e32 v2, s10
	v_add_co_u32_e32 v2, vcc, 0xe203000, v2
	v_mov_b32_e32 v3, s11
	s_nop 0
	v_addc_co_u32_e32 v3, vcc, 0, v3, vcc
	flat_atomic_add v2, v[2:3], v244 offset:1024 sc0

; __global__ void __launch_bounds__(NTHREADS, 2) mega_fwd(Args args) {
	.amdhsa_kernel _Z8mega_fwd4Args
		.amdhsa_group_segment_fixed_size 0
		.amdhsa_private_segment_fixed_size 0
		.amdhsa_kernarg_size 456
		.amdhsa_user_sgpr_count 2
		.amdhsa_user_sgpr_dispatch_ptr 0
		.amdhsa_user_sgpr_queue_ptr 0
		.amdhsa_user_sgpr_kernarg_segment_ptr 1
		.amdhsa_user_sgpr_dispatch_id 0
		.amdhsa_user_sgpr_kernarg_preload_length 0
		.amdhsa_user_sgpr_kernarg_preload_offset 0
		.amdhsa_user_sgpr_private_segment_size 0
		.amdhsa_uses_dynamic_stack 0
		.amdhsa_enable_private_segment 0
		.amdhsa_system_sgpr_workgroup_id_x 1
		.amdhsa_system_sgpr_workgroup_id_y 0
		.amdhsa_system_sgpr_workgroup_id_z 0
		.amdhsa_system_sgpr_workgroup_info 0
		.amdhsa_system_vgpr_workitem_id 2
		.amdhsa_next_free_vgpr 256
		.amdhsa_next_free_sgpr 102
		.amdhsa_accum_offset 256
		.amdhsa_reserve_vcc 1
		.amdhsa_float_round_mode_32 0
		.amdhsa_float_round_mode_16_64 0
		.amdhsa_float_denorm_mode_32 3
		.amdhsa_float_denorm_mode_16_64 3
		.amdhsa_dx10_clamp 1
		.amdhsa_ieee_mode 1
		.amdhsa_fp16_overflow 0
		.amdhsa_tg_split 0
		.amdhsa_exception_fp_ieee_invalid_op 0
		.amdhsa_exception_fp_denorm_src 0
		.amdhsa_exception_fp_ieee_div_zero 0
		.amdhsa_exception_fp_ieee_overflow 0
		.amdhsa_exception_fp_ieee_underflow 0
		.amdhsa_exception_fp_ieee_inexact 0
		.amdhsa_exception_int_div_zero 0
	.end_amdhsa_kernel

; __global__ void __launch_bounds__(NTHREADS, 2) mega_fwd(Args args) {
amdhsa.kernels:
  - .agpr_count:     0
    .args:
      - .offset:         0
        .size:           200
        .value_kind:     by_value
      - .offset:         200
        .size:           4
        .value_kind:     hidden_block_count_x
      - .offset:         204
        .size:           4
        .value_kind:     hidden_block_count_y
      - .offset:         208
        .size:           4
        .value_kind:     hidden_block_count_z
      - .offset:         212
        .size:           2
        .value_kind:     hidden_group_size_x
      - .offset:         214
        .size:           2
        .value_kind:     hidden_group_size_y
      - .offset:         216
        .size:           2
        .value_kind:     hidden_group_size_z
      - .offset:         218
        .size:           2
        .value_kind:     hidden_remainder_x
      - .offset:         220
        .size:           2
        .value_kind:     hidden_remainder_y
      - .offset:         222
        .size:           2
        .value_kind:     hidden_remainder_z
      - .offset:         240
        .size:           8
        .value_kind:     hidden_global_offset_x
      - .offset:         248
        .size:           8
        .value_kind:     hidden_global_offset_y
      - .offset:         256
        .size:           8
        .value_kind:     hidden_global_offset_z
      - .offset:         264
        .size:           2
        .value_kind:     hidden_grid_dims
      - .offset:         288
        .size:           8
        .value_kind:     hidden_multigrid_sync_arg
      - .offset:         320
        .size:           4
        .value_kind:     hidden_dynamic_lds_size
    .group_segment_fixed_size: 0
    .kernarg_segment_align: 8
    .kernarg_segment_size: 456
    .language:       OpenCL C
    .language_version:
      - 2
      - 0
    .max_flat_workgroup_size: 512
    .name:           _Z8mega_fwd4Args
    .private_segment_fixed_size: 0
    .sgpr_count:     108
    .sgpr_spill_count: 64
    .symbol:         _Z8mega_fwd4Args.kd
    .uniform_work_group_size: 1
    .uses_dynamic_stack: false
    .vgpr_count:     256
    .vgpr_spill_count: 0
    .wavefront_size: 64
